# plus: ret_prompt item bits permuted so the 8 value slices of a (batch,head) share an XCD; compress-stage-1 sample loop: kt+2 loads moved to the odd step
# speedup vs baseline: 1.0641x; 1.0034x over previous
.LBB0_1711:
	s_load_dwordx16 s[36:51], s[78:79], 0x100
	v_readlane_b32 s2, v252, 22
	s_cmp_lt_i32 s2, 5
	s_cselect_b64 s[18:19], -1, 0
	s_and_b64 s[0:1], s[18:19], s[0:1]
	s_waitcnt lgkmcnt(0)
	v_writelane_b32 v254, s36, 21
	s_andn2_b64 vcc, exec, s[0:1]
	v_readlane_b32 s3, v252, 23
	v_writelane_b32 v254, s37, 22
	v_writelane_b32 v254, s38, 23
	v_writelane_b32 v254, s39, 24
	v_writelane_b32 v254, s40, 25
	v_writelane_b32 v254, s41, 26
	v_writelane_b32 v254, s42, 27
	v_writelane_b32 v254, s43, 28
	v_writelane_b32 v254, s44, 29
	v_writelane_b32 v254, s45, 30
	v_writelane_b32 v254, s46, 31
	v_writelane_b32 v254, s47, 32
	v_writelane_b32 v254, s48, 33
	v_writelane_b32 v254, s49, 34
	v_writelane_b32 v254, s50, 35
	v_writelane_b32 v254, s51, 36
	s_cbranch_vccnz .LBB0_1783
	s_cmpk_gt_i32 s76, 0xff
	v_mov_b32_e32 v228, v248
	v_readfirstlane_b32 s0, v248
	s_cbranch_scc1 .LBB0_1756
	v_mov_b32_e32 v19, v228
	v_and_b32_e32 v2, 15, v19
	v_bfe_u32 v4, v19, 4, 2
	s_lshr_b32 s1, s0, 6
	v_lshl_or_b32 v1, s1, 4, v2
	v_lshlrev_b32_e32 v194, 3, v4
	s_lshl_b32 s2, s1, 16
	v_lshlrev_b32_e32 v5, 11, v2
	s_lshl_b32 s1, s1, 5
	v_or3_b32 v98, s2, v5, v194
	v_or_b32_e32 v5, s1, v2
	v_or_b32_e32 v7, 0x600, v19
	v_lshl_or_b32 v5, v5, 11, v194
	v_lshrrev_b32_e32 v199, 5, v7
	v_or_b32_e32 v7, 0xa00, v19
	v_or_b32_e32 v102, 0x8000, v5
	v_or_b32_e32 v104, 0x8020, v5
	v_or_b32_e32 v106, 0x8040, v5
	v_or_b32_e32 v108, 0x8060, v5
	v_lshlrev_b32_e32 v5, 3, v19
	v_lshrrev_b32_e32 v201, 5, v7
	v_or_b32_e32 v7, 0xe00, v19
	v_and_b32_e32 v196, 0xf8, v5
	v_or_b32_e32 v6, 0x200, v19
	v_lshrrev_b32_e32 v203, 5, v7
	v_lshlrev_b32_e32 v7, 7, v19
	v_and_b32_e32 v5, 0x78, v5
	s_mov_b32 s2, 0xf800
	v_lshlrev_b32_e32 v206, 2, v4
	v_lshlrev_b32_e32 v207, 1, v4
	v_lshrrev_b32_e32 v4, 4, v19
	v_mov_b32_e32 v101, 0
	v_and_or_b32 v204, v7, s2, v5
	s_add_i32 s2, 0, 0x18c00
	v_or_b32_e32 v100, s1, v206
	v_mul_u32_u24_e32 v16, 0x110, v4
	v_lshrrev_b32_e32 v4, 4, v6
	v_lshrrev_b32_e32 v197, 5, v6
	v_lshl_add_u32 v8, v5, 1, s2
	v_mul_u32_u24_e32 v6, 0x110, v4
	v_or_b32_e32 v4, 1, v100
	v_mov_b32_e32 v5, v101
	v_add3_u32 v11, s2, v194, v194
	s_and_b32 s2, s0, 0xffffffc0
	v_lshlrev_b64 v[226:227], 11, v[4:5]
	v_or_b32_e32 v4, 2, v100
	s_add_i32 s2, s2, 0
	v_lshlrev_b64 v[114:115], 11, v[4:5]
	v_or_b32_e32 v4, 3, v100
	v_and_b32_e32 v3, 63, v19
	s_add_u32 s10, s78, 0x2b0
	v_lshlrev_b64 v[116:117], 11, v[4:5]
	v_or_b32_e32 v4, 16, v100
	v_lshrrev_b32_e32 v195, 5, v19
	v_lshl_add_u32 v7, v196, 1, 0
	v_and_b32_e32 v9, 48, v19
	v_cmp_gt_u32_e64 s[4:5], 16, v3
	v_cmp_eq_u32_e64 s[6:7], 0, v3
	v_add_u32_e32 v3, s2, v194
	s_addc_u32 s11, s79, 0
	s_movk_i32 s1, 0x210
	s_movk_i32 s2, 0x110
	v_lshlrev_b64 v[118:119], 11, v[4:5]
	v_or_b32_e32 v4, 17, v100
	s_lshr_b32 s0, s0, 2
	s_mov_b32 s9, 0
	v_add_u32_e32 v10, 0, v9
	v_mad_u32_u24 v208, v195, s1, v7
	s_mov_b32 s1, 0x8400
	v_mul_u32_u24_e32 v12, 0x210, v197
	v_mul_u32_u24_e32 v13, 0x210, v199
	v_mul_u32_u24_e32 v14, 0x210, v201
	v_mul_u32_u24_e32 v15, 0x210, v203
	v_mul_u32_u24_e32 v17, 0x210, v2
	v_mul_u32_u24_e32 v18, 0x110, v2
	v_lshlrev_b64 v[250:251], 11, v[100:101]
	v_lshlrev_b64 v[120:121], 11, v[4:5]
	v_or_b32_e32 v4, 18, v100
	v_or_b32_e32 v100, 19, v100
	s_and_b32 s28, s0, 0x3fffffe0
	v_mad_u32_u24 v212, v2, s2, v194
	v_lshlrev_b32_e32 v126, 2, v2
	v_mbcnt_lo_u32_b32 v2, -1, 0
	s_mov_b32 s3, 16
	v_mov_b32_e32 v99, v101
	v_mov_b32_e32 v103, v101
	v_mov_b32_e32 v105, v101
	v_mov_b32_e32 v107, v101
	v_mov_b32_e32 v109, v101
	v_or_b32_e32 v198, 32, v195
	v_or_b32_e32 v200, 64, v195
	v_or_b32_e32 v202, 0x60, v195
	v_or_b32_e32 v205, 0x10000, v204
	v_add_u32_e32 v209, 0x8400, v208
	v_lshlrev_b64 v[122:123], 11, v[4:5]
	v_lshlrev_b64 v[124:125], 11, v[100:101]
	v_or_b32_e32 v210, 0xfffffe00, v19
	v_lshl_add_u32 v211, v19, 4, 0
	s_add_i32 s28, s28, 32
	v_add3_u32 v213, v17, v9, s1
	s_mov_b32 s29, 0xc2fc0000
	v_add_u32_e32 v214, v7, v12
	v_add_u32_e32 v215, v7, v13
	v_add_u32_e32 v216, v7, v14
	v_add_u32_e32 v217, v7, v15
	v_add_u32_e32 v218, v8, v16
	v_add_u32_e32 v219, v8, v6
	v_add_u32_e32 v220, v10, v17
	v_add_u32_e32 v221, v11, v18
	v_mov_b32_e32 v222, 1
	v_mov_b32_e32 v223, 0x358637bd
	s_mov_b32 s30, 0xf800000
	v_mov_b32_e32 v224, 0x260
	v_add_u32_e32 v225, v3, v17
	s_mov_b32 s2, s9
	v_mov_b32_e32 v238, v101
	v_mov_b32_e32 v239, v101
	v_mov_b32_e32 v240, v101
	v_mov_b32_e32 v241, v101
	v_mov_b32_e32 v229, 0x42800000
	v_mbcnt_hi_u32_b32 v230, -1, v2
	s_and_b32 s31, s76, 7
	s_lshl_b32 s31, s31, 5
	s_bfe_u32 s98, s76, 0x20006
	s_lshl_b32 s98, s98, 3
	s_or_b32 s31, s31, s98
	s_bfe_u32 s98, s76, 0x30003
	s_or_b32 s31, s31, s98
	s_branch .LBB0_1716

.LBB0_4029:
	s_waitcnt vmcnt(0)
	v_cvt_pk_bf16_f32 v168, v22, v23
	v_cvt_pk_bf16_f32 v169, v24, v25
	v_cvt_pk_bf16_f32 v170, v18, v19
	v_cvt_pk_bf16_f32 v171, v20, v21
	s_barrier
	ds_write_b128 v184, v[168:171]
	s_waitcnt vmcnt(4)
	v_cvt_pk_bf16_f32 v168, v30, v31
	v_cvt_pk_bf16_f32 v169, v32, v33
	v_cvt_pk_bf16_f32 v170, v26, v27
	v_cvt_pk_bf16_f32 v171, v28, v29
	s_cmp_lt_u32 s17, 7
	ds_write_b128 v185, v[168:171]
	s_waitcnt vmcnt(3)
	ds_write_b128 v184, v[54:57] offset:18432
	s_waitcnt vmcnt(2)
	ds_write_b128 v185, v[50:53] offset:18432
	s_waitcnt vmcnt(1)
	ds_write_b128 v184, v[58:61] offset:36864
	s_waitcnt vmcnt(0)
	ds_write_b128 v186, v[62:65] offset:18432
	s_cselect_b64 s[12:13], -1, 0
	s_cmp_gt_u32 s17, 6
	v_lshl_add_u64 v[168:169], v[166:167], 0, v[130:131]
	v_lshl_add_u64 v[170:171], v[164:165], 0, v[130:131]
	s_waitcnt lgkmcnt(0)
	s_barrier
	s_cbranch_scc1 .LBB0_4031
.LBB0_4031:
	ds_read_b128 v[50:53], v188 offset:18432
	ds_read_b128 v[54:57], v187
	ds_read_b128 v[58:61], v187 offset:64
	ds_read_b128 v[190:193], v188 offset:18496
	v_lshl_add_u64 v[176:177], v[156:157], 0, s[10:11]
	v_lshl_add_u64 v[182:183], v[162:163], 0, s[10:11]
	s_waitcnt lgkmcnt(2)
	v_mfma_f32_16x16x32_bf16 v[62:65], v[50:53], v[54:57], v[114:117]
	s_nop 2
	ds_read_b128 v[114:117], v188 offset:20736
	ds_read_b128 v[194:197], v188 offset:20800
	ds_read_b128 v[172:175], v188 offset:23040
	ds_read_b128 v[198:201], v188 offset:23104
	ds_read_b128 v[202:205], v188 offset:25344
	ds_read_b128 v[206:209], v188 offset:25408
	s_waitcnt lgkmcnt(5)
	v_mfma_f32_16x16x32_bf16 v[126:129], v[114:117], v[54:57], v[126:129]
	s_andn2_b64 vcc, exec, s[12:13]
	s_waitcnt lgkmcnt(3)
	v_mfma_f32_16x16x32_bf16 v[122:125], v[172:175], v[54:57], v[122:125]
	s_waitcnt lgkmcnt(1)
	v_mfma_f32_16x16x32_bf16 v[54:57], v[202:205], v[54:57], v[118:121]
	s_nop 2
	ds_read_b128 v[118:121], v187 offset:2304
	ds_read_b128 v[210:213], v187 offset:2368
	s_waitcnt lgkmcnt(1)
	v_mfma_f32_16x16x32_bf16 v[110:113], v[50:53], v[118:121], v[110:113]
	v_mfma_f32_16x16x32_bf16 v[102:105], v[114:117], v[118:121], v[102:105]
	v_mfma_f32_16x16x32_bf16 v[94:97], v[172:175], v[118:121], v[94:97]
	v_mfma_f32_16x16x32_bf16 v[118:121], v[202:205], v[118:121], v[90:93]
	s_nop 2
	ds_read_b128 v[90:93], v187 offset:4608
	ds_read_b128 v[214:217], v187 offset:4672
	s_waitcnt lgkmcnt(1)
	v_mfma_f32_16x16x32_bf16 v[228:231], v[172:175], v[90:93], v[70:73]
	s_nop 2
	ds_read_b128 v[70:73], v187 offset:6912
	ds_read_b128 v[232:235], v187 offset:6976
	s_waitcnt lgkmcnt(1)
	v_mfma_f32_16x16x32_bf16 v[244:247], v[172:175], v[70:73], v[106:109]
	v_lshl_add_u64 v[172:173], v[152:153], 0, s[10:11]
	v_lshl_add_u64 v[174:175], v[154:155], 0, s[10:11]
	v_mfma_f32_16x16x32_bf16 v[218:221], v[50:53], v[90:93], v[86:89]
	v_mfma_f32_16x16x32_bf16 v[222:225], v[114:117], v[90:93], v[78:81]
	v_mfma_f32_16x16x32_bf16 v[66:69], v[202:205], v[90:93], v[66:69]
	v_mfma_f32_16x16x32_bf16 v[236:239], v[50:53], v[70:73], v[82:85]
	v_mfma_f32_16x16x32_bf16 v[240:243], v[114:117], v[70:73], v[74:77]
	s_waitcnt vmcnt(3)
	v_cvt_pk_bf16_f32 v114, v34, v35
	v_cvt_pk_bf16_f32 v115, v36, v37
	s_waitcnt vmcnt(2)
	v_cvt_pk_bf16_f32 v116, v38, v39
	v_mfma_f32_16x16x32_bf16 v[202:205], v[202:205], v[70:73], v[98:101]
	v_cvt_pk_bf16_f32 v117, v40, v41
	v_mfma_f32_16x16x32_bf16 v[70:73], v[190:193], v[58:61], v[62:65]
	v_mfma_f32_16x16x32_bf16 v[74:77], v[194:197], v[58:61], v[126:129]
	v_mfma_f32_16x16x32_bf16 v[78:81], v[198:201], v[58:61], v[122:125]
	v_mfma_f32_16x16x32_bf16 v[82:85], v[206:209], v[58:61], v[54:57]
	s_nop 2
	global_load_dwordx4 v[54:57], v[172:173], off offset:128
	global_load_dwordx4 v[50:53], v[174:175], off offset:128
	global_load_dwordx4 v[58:61], v[176:177], off offset:128
	global_load_dwordx4 v[62:65], v[182:183], off offset:128
	v_mfma_f32_16x16x32_bf16 v[98:101], v[206:209], v[210:213], v[118:121]
	s_waitcnt vmcnt(5)
	v_cvt_pk_bf16_f32 v118, v42, v43
	v_cvt_pk_bf16_f32 v119, v44, v45
	s_waitcnt vmcnt(4)
	v_cvt_pk_bf16_f32 v120, v46, v47
	v_cvt_pk_bf16_f32 v121, v48, v49
	v_mfma_f32_16x16x32_bf16 v[86:89], v[190:193], v[210:213], v[110:113]
	s_waitcnt lgkmcnt(0)
	s_barrier
	v_mfma_f32_16x16x32_bf16 v[90:93], v[194:197], v[210:213], v[102:105]
	ds_write_b128 v184, v[114:117]
	ds_write_b128 v185, v[118:121]
	s_waitcnt vmcnt(3)
	ds_write_b128 v184, v[54:57] offset:18432
	s_waitcnt vmcnt(2)
	ds_write_b128 v185, v[50:53] offset:18432
	s_waitcnt vmcnt(1)
	ds_write_b128 v184, v[58:61] offset:36864
	v_mfma_f32_16x16x32_bf16 v[94:97], v[198:201], v[210:213], v[94:97]
	s_waitcnt vmcnt(0)
	ds_write_b128 v186, v[62:65] offset:18432
	s_waitcnt lgkmcnt(0)
	s_barrier
	v_mfma_f32_16x16x32_bf16 v[102:105], v[190:193], v[214:217], v[218:221]
	v_mfma_f32_16x16x32_bf16 v[106:109], v[194:197], v[214:217], v[222:225]
	v_mfma_f32_16x16x32_bf16 v[110:113], v[198:201], v[214:217], v[228:231]
	v_mfma_f32_16x16x32_bf16 v[114:117], v[206:209], v[214:217], v[66:69]
	v_mfma_f32_16x16x32_bf16 v[118:121], v[190:193], v[232:235], v[236:239]
	v_mfma_f32_16x16x32_bf16 v[122:125], v[194:197], v[232:235], v[240:243]
	v_mfma_f32_16x16x32_bf16 v[126:129], v[198:201], v[232:235], v[244:247]
	v_mfma_f32_16x16x32_bf16 v[66:69], v[206:209], v[232:235], v[202:205]
	s_cbranch_vccnz .LBB0_4033
	v_add_co_u32_e32 v34, vcc, 0x3000, v170
	v_lshl_add_u64 v[46:47], v[168:169], 0, s[8:9]
	s_nop 0
	v_addc_co_u32_e32 v35, vcc, 0, v171, vcc
	v_add_co_u32_e32 v42, vcc, 0x3000, v168
	v_lshl_add_u64 v[38:39], v[170:171], 0, s[8:9]
	s_nop 0
	v_addc_co_u32_e32 v43, vcc, 0, v169, vcc
	global_load_dwordx4 v[34:37], v[34:35], off
	s_nop 0
	global_load_dwordx4 v[38:41], v[38:39], off offset:16
	s_nop 0
	global_load_dwordx4 v[42:45], v[42:43], off
	s_nop 0
	global_load_dwordx4 v[46:49], v[46:47], off offset:16
	v_add_co_u32_e32 v20, vcc, 0x2000, v170
	v_lshl_add_u64 v[26:27], v[168:169], 0, s[6:7]
	s_nop 0
	v_addc_co_u32_e32 v21, vcc, 0, v171, vcc
	v_add_co_u32_e32 v28, vcc, 0x2000, v168
	v_lshl_add_u64 v[18:19], v[170:171], 0, s[6:7]
	s_nop 0
	v_addc_co_u32_e32 v29, vcc, 0, v169, vcc
	global_load_dwordx4 v[22:25], v[20:21], off
	s_nop 0
	global_load_dwordx4 v[18:21], v[18:19], off offset:16
	s_nop 0
	global_load_dwordx4 v[30:33], v[28:29], off
	s_nop 0
	global_load_dwordx4 v[26:29], v[26:27], off offset:16

.LBB0_4039:
	s_waitcnt vmcnt(0)
	v_cvt_pk_bf16_f32 v162, v22, v23
	v_cvt_pk_bf16_f32 v163, v24, v25
	v_cvt_pk_bf16_f32 v164, v18, v19
	v_cvt_pk_bf16_f32 v165, v20, v21
	s_barrier
	ds_write_b128 v184, v[162:165]
	s_waitcnt vmcnt(4)
	v_cvt_pk_bf16_f32 v162, v34, v35
	v_cvt_pk_bf16_f32 v163, v36, v37
	v_cvt_pk_bf16_f32 v164, v30, v31
	v_cvt_pk_bf16_f32 v165, v32, v33
	s_cmp_lt_u32 s17, 7
	ds_write_b128 v185, v[162:165]
	s_waitcnt vmcnt(3)
	ds_write_b128 v184, v[54:57] offset:18432
	s_waitcnt vmcnt(2)
	ds_write_b128 v185, v[58:61] offset:18432
	s_waitcnt vmcnt(1)
	ds_write_b128 v184, v[62:65] offset:36864
	s_waitcnt vmcnt(0)
	ds_write_b128 v186, v[66:69] offset:18432
	s_cselect_b64 s[12:13], -1, 0
	s_cmp_gt_u32 s17, 6
	v_lshl_add_u64 v[162:163], v[160:161], 0, v[130:131]
	v_lshl_add_u64 v[164:165], v[158:159], 0, v[130:131]
	s_waitcnt lgkmcnt(0)
	s_barrier
	s_cbranch_scc1 .LBB0_4041
.LBB0_4041:
	ds_read_b128 v[54:57], v188 offset:18432
	ds_read_b128 v[58:61], v187
	ds_read_b128 v[66:69], v188 offset:20736
	ds_read_b128 v[166:169], v188 offset:23040
	ds_read_b128 v[174:177], v188 offset:25344
	s_andn2_b64 vcc, exec, s[12:13]
	s_waitcnt lgkmcnt(3)
	v_mfma_f32_16x16x32_bf16 v[62:65], v[54:57], v[58:61], v[126:129]
	ds_read_b128 v[198:201], v188 offset:20800
	ds_read_b128 v[202:205], v187 offset:2368
	s_waitcnt lgkmcnt(4)
	v_mfma_f32_16x16x32_bf16 v[126:129], v[66:69], v[58:61], v[122:125]
	s_waitcnt lgkmcnt(3)
	v_mfma_f32_16x16x32_bf16 v[170:173], v[166:169], v[58:61], v[118:121]
	s_waitcnt lgkmcnt(2)
	v_mfma_f32_16x16x32_bf16 v[58:61], v[174:177], v[58:61], v[114:117]
	s_nop 2
	ds_read_b128 v[114:117], v187 offset:2304
	s_waitcnt lgkmcnt(0)
	v_mfma_f32_16x16x32_bf16 v[194:197], v[174:177], v[114:117], v[98:101]
	s_nop 2
	ds_read_b128 v[98:101], v187 offset:4608
	v_mfma_f32_16x16x32_bf16 v[190:193], v[54:57], v[114:117], v[110:113]
	s_waitcnt lgkmcnt(0)
	v_mfma_f32_16x16x32_bf16 v[110:113], v[174:177], v[98:101], v[78:81]
	s_nop 2
	ds_read_b128 v[78:81], v187 offset:6912
	v_mfma_f32_16x16x32_bf16 v[106:109], v[66:69], v[114:117], v[106:109]
	v_mfma_f32_16x16x32_bf16 v[102:105], v[166:169], v[114:117], v[102:105]
	v_mfma_f32_16x16x32_bf16 v[122:125], v[54:57], v[98:101], v[94:97]
	v_mfma_f32_16x16x32_bf16 v[118:121], v[66:69], v[98:101], v[90:93]
	v_mfma_f32_16x16x32_bf16 v[114:117], v[166:169], v[98:101], v[82:85]
	s_waitcnt lgkmcnt(0)
	v_mfma_f32_16x16x32_bf16 v[98:101], v[54:57], v[78:81], v[74:77]
	ds_read_b128 v[54:57], v187 offset:64
	v_mfma_f32_16x16x32_bf16 v[90:93], v[66:69], v[78:81], v[70:73]
	v_lshl_add_u64 v[66:67], v[144:145], 0, s[10:11]
	global_load_dwordx4 v[66:69], v[66:67], off
	v_mfma_f32_16x16x32_bf16 v[82:85], v[166:169], v[78:81], v[86:89]
	ds_read_b128 v[166:169], v188 offset:18496
	s_waitcnt lgkmcnt(1)
	v_mfma_f32_16x16x32_bf16 v[70:73], v[198:201], v[54:57], v[126:129]
	s_nop 2
	ds_read_b128 v[126:129], v188 offset:23104
	s_waitcnt lgkmcnt(0)
	v_mfma_f32_16x16x32_bf16 v[74:77], v[126:129], v[54:57], v[170:173]
	s_nop 2
	ds_read_b128 v[170:173], v188 offset:25408
	v_mfma_f32_16x16x32_bf16 v[174:177], v[174:177], v[78:81], v[50:53]
	v_mfma_f32_16x16x32_bf16 v[50:53], v[166:169], v[54:57], v[62:65]
	s_waitcnt lgkmcnt(0)
	v_mfma_f32_16x16x32_bf16 v[78:81], v[170:173], v[54:57], v[58:61]
	v_lshl_add_u64 v[54:55], v[148:149], 0, s[10:11]
	v_lshl_add_u64 v[62:63], v[146:147], 0, s[10:11]
	global_load_dwordx4 v[54:57], v[54:55], off
	v_lshl_add_u64 v[58:59], v[138:139], 0, s[10:11]
	global_load_dwordx4 v[58:61], v[58:59], off
	v_mfma_f32_16x16x32_bf16 v[86:89], v[166:169], v[202:205], v[190:193]
	global_load_dwordx4 v[62:65], v[62:63], off
	v_mfma_f32_16x16x32_bf16 v[94:97], v[198:201], v[202:205], v[106:109]
	v_mfma_f32_16x16x32_bf16 v[106:109], v[170:173], v[202:205], v[194:197]
	ds_read_b128 v[190:193], v187 offset:4672
	s_nop 1
	ds_read_b128 v[194:197], v187 offset:6976
	s_waitcnt lgkmcnt(0)
	s_barrier
	v_mfma_f32_16x16x32_bf16 v[102:105], v[126:129], v[202:205], v[102:105]
	s_waitcnt vmcnt(7)
	v_cvt_pk_bf16_f32 v202, v26, v27
	v_cvt_pk_bf16_f32 v203, v28, v29
	s_waitcnt vmcnt(6)
	v_cvt_pk_bf16_f32 v204, v38, v39
	v_mfma_f32_16x16x32_bf16 v[122:125], v[166:169], v[190:193], v[122:125]
	v_cvt_pk_bf16_f32 v205, v40, v41
	ds_write_b128 v184, v[202:205]
	v_mfma_f32_16x16x32_bf16 v[118:121], v[198:201], v[190:193], v[118:121]
	s_waitcnt vmcnt(5)
	v_cvt_pk_bf16_f32 v202, v42, v43
	v_cvt_pk_bf16_f32 v203, v44, v45
	s_waitcnt vmcnt(4)
	v_cvt_pk_bf16_f32 v204, v46, v47
	v_mfma_f32_16x16x32_bf16 v[114:117], v[126:129], v[190:193], v[114:117]
	v_cvt_pk_bf16_f32 v205, v48, v49
	ds_write_b128 v185, v[202:205]
	s_waitcnt vmcnt(2)
	ds_write_b128 v184, v[54:57] offset:18432
	s_waitcnt vmcnt(1)
	ds_write_b128 v185, v[58:61] offset:18432
	s_waitcnt vmcnt(0)
	ds_write_b128 v184, v[62:65] offset:36864
	v_mfma_f32_16x16x32_bf16 v[110:113], v[170:173], v[190:193], v[110:113]
	ds_write_b128 v186, v[66:69] offset:18432
	s_waitcnt lgkmcnt(0)
	s_barrier
	v_mfma_f32_16x16x32_bf16 v[98:101], v[166:169], v[194:197], v[98:101]
	v_mfma_f32_16x16x32_bf16 v[90:93], v[198:201], v[194:197], v[90:93]
	v_mfma_f32_16x16x32_bf16 v[82:85], v[126:129], v[194:197], v[82:85]
	v_mfma_f32_16x16x32_bf16 v[126:129], v[170:173], v[194:197], v[174:177]
	s_cbranch_vccnz .LBB0_4043
	v_add_co_u32_e32 v26, vcc, 0x3000, v164
	v_lshl_add_u64 v[46:47], v[162:163], 0, s[6:7]
	s_nop 0
	v_addc_co_u32_e32 v27, vcc, 0, v165, vcc
	v_add_co_u32_e32 v42, vcc, 0x3000, v162
	v_lshl_add_u64 v[38:39], v[164:165], 0, s[6:7]
	s_nop 0
	v_addc_co_u32_e32 v43, vcc, 0, v163, vcc
	global_load_dwordx4 v[26:29], v[26:27], off offset:1024
	s_nop 0
	global_load_dwordx4 v[38:41], v[38:39], off offset:16
	s_nop 0
	global_load_dwordx4 v[42:45], v[42:43], off offset:1024
	s_nop 0
	global_load_dwordx4 v[46:49], v[46:47], off offset:16
	v_add_co_u32_e32 v20, vcc, 0x2000, v164
	v_lshl_add_u64 v[30:31], v[162:163], 0, s[4:5]
	s_nop 0
	v_addc_co_u32_e32 v21, vcc, 0, v165, vcc
	v_add_co_u32_e32 v32, vcc, 0x2000, v162
	v_lshl_add_u64 v[18:19], v[164:165], 0, s[4:5]
	s_nop 0
	v_addc_co_u32_e32 v33, vcc, 0, v163, vcc
	global_load_dwordx4 v[22:25], v[20:21], off offset:1024
	s_nop 0
	global_load_dwordx4 v[18:21], v[18:19], off offset:16
	s_nop 0
	global_load_dwordx4 v[34:37], v[32:33], off offset:1024
	s_nop 0
	global_load_dwordx4 v[30:33], v[30:31], off offset:16

	.amdhsa_kernel _Z4mega6Params
		.amdhsa_group_segment_fixed_size 0
		.amdhsa_private_segment_fixed_size 0
		.amdhsa_kernarg_size 944
		.amdhsa_user_sgpr_count 2
		.amdhsa_user_sgpr_dispatch_ptr 0
		.amdhsa_user_sgpr_queue_ptr 0
		.amdhsa_user_sgpr_kernarg_segment_ptr 1
		.amdhsa_user_sgpr_dispatch_id 0
		.amdhsa_user_sgpr_kernarg_preload_length 0
		.amdhsa_user_sgpr_kernarg_preload_offset 0
		.amdhsa_user_sgpr_private_segment_size 0
		.amdhsa_uses_dynamic_stack 0
		.amdhsa_enable_private_segment 0
		.amdhsa_system_sgpr_workgroup_id_x 1
		.amdhsa_system_sgpr_workgroup_id_y 0
		.amdhsa_system_sgpr_workgroup_id_z 0
		.amdhsa_system_sgpr_workgroup_info 0
		.amdhsa_system_vgpr_workitem_id 0
		.amdhsa_next_free_vgpr 256
		.amdhsa_next_free_sgpr 102
		.amdhsa_accum_offset 256
		.amdhsa_reserve_vcc 1
		.amdhsa_float_round_mode_32 0
		.amdhsa_float_round_mode_16_64 0
		.amdhsa_float_denorm_mode_32 3
		.amdhsa_float_denorm_mode_16_64 3
		.amdhsa_dx10_clamp 1
		.amdhsa_ieee_mode 1
		.amdhsa_fp16_overflow 0
		.amdhsa_tg_split 0
		.amdhsa_exception_fp_ieee_invalid_op 0
		.amdhsa_exception_fp_denorm_src 0
		.amdhsa_exception_fp_ieee_div_zero 0
		.amdhsa_exception_fp_ieee_overflow 0
		.amdhsa_exception_fp_ieee_underflow 0
		.amdhsa_exception_fp_ieee_inexact 0
		.amdhsa_exception_int_div_zero 0
	.end_amdhsa_kernel

amdhsa.kernels:
  - .agpr_count:     0
    .args:
      - .offset:         0
        .size:           688
        .value_kind:     by_value
      - .offset:         688
        .size:           4
        .value_kind:     hidden_block_count_x
      - .offset:         692
        .size:           4
        .value_kind:     hidden_block_count_y
      - .offset:         696
        .size:           4
        .value_kind:     hidden_block_count_z
      - .offset:         700
        .size:           2
        .value_kind:     hidden_group_size_x
      - .offset:         702
        .size:           2
        .value_kind:     hidden_group_size_y
      - .offset:         704
        .size:           2
        .value_kind:     hidden_group_size_z
      - .offset:         706
        .size:           2
        .value_kind:     hidden_remainder_x
      - .offset:         708
        .size:           2
        .value_kind:     hidden_remainder_y
      - .offset:         710
        .size:           2
        .value_kind:     hidden_remainder_z
      - .offset:         728
        .size:           8
        .value_kind:     hidden_global_offset_x
      - .offset:         736
        .size:           8
        .value_kind:     hidden_global_offset_y
      - .offset:         744
        .size:           8
        .value_kind:     hidden_global_offset_z
      - .offset:         752
        .size:           2
        .value_kind:     hidden_grid_dims
      - .offset:         808
        .size:           4
        .value_kind:     hidden_dynamic_lds_size
    .group_segment_fixed_size: 0
    .kernarg_segment_align: 8
    .kernarg_segment_size: 944
    .language:       OpenCL C
    .language_version:
      - 2
      - 0
    .max_flat_workgroup_size: 512
    .name:           _Z4mega6Params
    .private_segment_fixed_size: 0
    .sgpr_count:     108
    .sgpr_spill_count: 378
    .symbol:         _Z4mega6Params.kd
    .uniform_work_group_size: 1
    .uses_dynamic_stack: false
    .vgpr_count:     256
    .vgpr_spill_count: 0
    .wavefront_size: 64
